# stick sample path: cache_c_k / cache_c_v rows (read once) loaded with the nt hint
# speedup vs baseline: 1.0072x; 1.0072x over previous
.LBB0_582:
	s_or_b64 exec, exec, s[10:11]
	v_cmp_ne_u64_e32 vcc, 0, v[48:49]
	v_mov_b32_e32 v26, 0
	v_mov_b32_e32 v53, 0
	v_mov_b32_e32 v50, 0
	v_mov_b32_e32 v44, 0
	v_mov_b32_e32 v0, 0
	v_mov_b32_e32 v55, 0
	v_mov_b32_e32 v54, 0
	v_mov_b32_e32 v52, 0
	v_mov_b32_e32 v46, 0
	v_mov_b32_e32 v27, 0
	v_mov_b32_e32 v28, 0
	v_mov_b32_e32 v29, 0
	v_mov_b32_e32 v30, 0
	v_mov_b32_e32 v31, 0
	v_mov_b32_e32 v32, 0
	v_mov_b32_e32 v33, 0
	s_and_saveexec_b64 s[10:11], vcc
	s_cbranch_execz .LBB0_584
	global_load_dwordx4 v[26:29], v[48:49], off nt
	global_load_dwordx4 v[52:55], v[48:49], off offset:16 nt
	global_load_dwordx4 v[56:59], v[48:49], off offset:32 nt
	global_load_dwordx4 v[62:65], v[48:49], off offset:48 nt
	global_load_dwordx4 v[66:69], v[34:35], off nt
	global_load_dwordx4 v[90:93], v[34:35], off offset:16 nt
	global_load_dwordx4 v[94:97], v[34:35], off offset:32 nt
	global_load_dwordx4 v[98:101], v[34:35], off offset:48 nt
	s_waitcnt vmcnt(7)
	v_cvt_pk_bf16_f32 v30, v26, v27
	v_cvt_pk_bf16_f32 v31, v28, v29
	s_waitcnt vmcnt(6)
	v_cvt_pk_bf16_f32 v32, v52, v53
	v_cvt_pk_bf16_f32 v33, v54, v55
	s_waitcnt vmcnt(5)
	v_cvt_pk_bf16_f32 v26, v56, v57
	v_cvt_pk_bf16_f32 v27, v58, v59
	s_waitcnt vmcnt(4)
	v_cvt_pk_bf16_f32 v28, v62, v63
	v_cvt_pk_bf16_f32 v29, v64, v65
	s_waitcnt vmcnt(3)
	v_cvt_pk_bf16_f32 v55, v66, v67
	v_cvt_pk_bf16_f32 v54, v68, v69
	s_waitcnt vmcnt(2)
	v_cvt_pk_bf16_f32 v52, v90, v91
	v_cvt_pk_bf16_f32 v46, v92, v93
	s_waitcnt vmcnt(1)
	v_cvt_pk_bf16_f32 v53, v94, v95
	v_cvt_pk_bf16_f32 v50, v96, v97
	s_waitcnt vmcnt(0)
	v_cvt_pk_bf16_f32 v44, v98, v99
	v_cvt_pk_bf16_f32 v0, v100, v101
